# v28 + nt on the f32 x loads in the W_out GEMM epilogue (last use of x)
# speedup vs baseline: 1.0053x; 1.0018x over previous
; __device__ __forceinline__ unsigned pkbf(float lo, float hi) { return pg8::cvt_pk_bf16(lo, hi); }
; __device__ __forceinline__ void unpack8bf(const u32x4 w, float* f) { f[0] = bflo(w.x); f[1] = bfhi(w.x); f[2] = bflo(w.y); f[3] = bfhi(w.y); f[4] = bflo(w.z); f[5] = bfhi(w.z); f[6] = bflo(w.w); f[7] = bfhi(w.w); }
;     __device__ __forceinline__ void operator()(AccRef acc, const Unit& u, int wr, int wc, int fr, int fq) const {
;         asm volatile("" : "+v"(fr), "+v"(fq));
;         const int row0 = u.pm * 256 + wr * 64 + fr, col0 = u.pn * 256 + wc * 32 + 8 * fq;
;         const float* xb = (u.pm * 256 < TP) ? xp : xs - (size_t)TP * DM;
; #pragma unroll
;         for (int ai = 0; ai < 2; ++ai)
; #pragma unroll
;             for (int m = 0; m < 4; ++m)
; #pragma unroll
;                 for (int bj = 0; bj < 2; ++bj) {
;                     const size_t off = (size_t)(row0 + ai * 128 + m * 16) * DM + col0 + bj * 128;
;                     const f32x4 x0 = *(const f32x4*)(xb + off), x1 = *(const f32x4*)(xb + off + 4);
;                     const u32x4 dw = *(const u32x4*)(D1 + off); float d[8]; unpack8bf(dw, d);
;                     float o[8];
; #pragma unroll
;                     for (int e = 0; e < 4; ++e) { o[e] = x0[e] + d[e] + acc[ai][bj][m][0][e]; o[4 + e] = x1[e] + d[4 + e] + acc[ai][bj][m][1][e]; }
;                     u32x4 w; w.x = pkbf(o[0], o[1]); w.y = pkbf(o[2], o[3]); w.z = pkbf(o[4], o[5]); w.w = pkbf(o[6], o[7]);
;                     *(u32x4*)(D1 + off) = w;
;                 }
;     }
.LBB0_1244:
	v_mov_b32_e32 v147, v148
	v_mov_b32_e32 v146, v129
	s_lshl_b32 s4, s58, 8
	s_add_i32 s4, s4, s68
	v_add_u32_e32 v146, s4, v146
	s_lshl_b32 s4, s78, 8
	s_or_b32 s4, s4, s69
	v_lshl_add_u32 v154, v147, 3, s4
	v_ashrrev_i32_e32 v147, 31, v146
	v_ashrrev_i32_e32 v155, 31, v154
	v_lshlrev_b64 v[146:147], 10, v[146:147]
	v_readlane_b32 s4, v237, 5
	v_lshl_add_u64 v[146:147], v[146:147], 0, v[154:155]
	s_cmpk_lt_i32 s58, 0x80
	v_readlane_b32 s5, v237, 6
	v_lshl_add_u64 v[162:163], v[146:147], 1, s[30:31]
	s_cselect_b32 s5, s5, s72
	s_cselect_b32 s4, s4, s71
	global_load_dwordx4 v[154:157], v[162:163], off
	v_lshl_add_u64 v[172:173], v[146:147], 2, s[4:5]
	global_load_dwordx4 v[158:161], v[172:173], off nt
	global_load_dwordx4 v[168:171], v[172:173], off offset:16 nt
	v_readlane_b32 s10, v237, 11
	v_readlane_b32 s11, v237, 12
	s_mov_b64 s[10:11], 0x4000
	s_and_b64 vcc, exec, s[46:47]
	v_readlane_b32 s6, v237, 7
	v_readlane_b32 s7, v237, 8
	v_readlane_b32 s8, v237, 9
	v_readlane_b32 s9, v237, 10
	v_readlane_b32 s12, v237, 13
	v_readlane_b32 s13, v237, 14
	v_readlane_b32 s14, v237, 15
	v_readlane_b32 s15, v237, 16
	v_readlane_b32 s16, v237, 17
	v_readlane_b32 s17, v237, 18
	v_readlane_b32 s18, v237, 19
	v_readlane_b32 s19, v237, 20
	s_waitcnt vmcnt(0)
	v_lshlrev_b32_e32 v153, 16, v154
	v_and_b32_e32 v154, 0xffff0000, v154
	v_lshlrev_b32_e32 v165, 16, v155
	v_and_b32_e32 v155, 0xffff0000, v155
	v_lshlrev_b32_e32 v166, 16, v156
	v_and_b32_e32 v156, 0xffff0000, v156
	v_lshlrev_b32_e32 v174, 16, v157
	v_and_b32_e32 v157, 0xffff0000, v157
	v_add_f32_e32 v153, v158, v153
	v_add_f32_e32 v158, v168, v166
	v_add_f32_e32 v154, v159, v154
	v_add_f32_e32 v156, v169, v156
	v_add_f32_e32 v159, v160, v165
	v_add_f32_e32 v160, v170, v174
	v_add_f32_e32 v155, v161, v155
	v_add_f32_e32 v157, v171, v157
	v_add_f32_e32 v120, v120, v153
	v_add_f32_e32 v124, v124, v158
	v_add_f32_e32 v121, v121, v154
	v_add_f32_e32 v125, v125, v156
	v_add_f32_e32 v122, v122, v159
	v_add_f32_e32 v126, v126, v160
	v_add_f32_e32 v123, v123, v155
	v_add_f32_e32 v127, v127, v157
	v_cvt_pk_bf16_f32 v120, v120, v121
	v_cvt_pk_bf16_f32 v121, v122, v123
	v_cvt_pk_bf16_f32 v122, v124, v125
	v_cvt_pk_bf16_f32 v123, v126, v127
	global_load_dwordx4 v[124:127], v[162:163], off offset:256
	v_lshl_add_u64 v[158:159], v[146:147], 0, s[10:11]
	global_store_dwordx4 v[162:163], v[120:123], off
	global_load_dwordx4 v[120:123], v[172:173], off offset:512 nt
	s_nop 0
	global_load_dwordx4 v[154:157], v[172:173], off offset:528 nt
	v_lshl_add_u64 v[160:161], v[158:159], 1, s[30:31]
	s_waitcnt vmcnt(0)
	v_lshlrev_b32_e32 v153, 16, v124
	v_and_b32_e32 v124, 0xffff0000, v124
	v_lshlrev_b32_e32 v165, 16, v125
	v_and_b32_e32 v125, 0xffff0000, v125
	v_lshlrev_b32_e32 v166, 16, v126
	v_and_b32_e32 v126, 0xffff0000, v126
	v_lshlrev_b32_e32 v168, 16, v127
	v_and_b32_e32 v127, 0xffff0000, v127
	v_add_f32_e32 v120, v120, v153
	v_add_f32_e32 v153, v154, v166
	v_add_f32_e32 v121, v121, v124
	v_add_f32_e32 v124, v155, v126
	v_add_f32_e32 v122, v122, v165
	v_add_f32_e32 v126, v156, v168
	v_add_f32_e32 v123, v123, v125
	v_add_f32_e32 v125, v157, v127
	v_add_f32_e32 v116, v116, v120
	v_add_f32_e32 v120, v112, v153
	v_add_f32_e32 v112, v117, v121
	v_add_f32_e32 v117, v113, v124
	v_add_f32_e32 v113, v118, v122
	v_add_f32_e32 v118, v114, v126
	v_add_f32_e32 v114, v119, v123
	v_add_f32_e32 v115, v115, v125
	v_cvt_pk_bf16_f32 v112, v116, v112
	v_cvt_pk_bf16_f32 v113, v113, v114
	v_cvt_pk_bf16_f32 v114, v120, v117
	v_cvt_pk_bf16_f32 v115, v118, v115
	global_store_dwordx4 v[162:163], v[112:115], off offset:256
	global_load_dwordx4 v[112:115], v[160:161], off
	v_lshl_add_u64 v[124:125], v[158:159], 2, s[4:5]
	global_load_dwordx4 v[116:119], v[124:125], off nt
	global_load_dwordx4 v[120:123], v[124:125], off offset:16 nt
	s_waitcnt vmcnt(0)
	v_lshlrev_b32_e32 v126, 16, v112
	v_and_b32_e32 v112, 0xffff0000, v112
	v_lshlrev_b32_e32 v127, 16, v113
	v_and_b32_e32 v113, 0xffff0000, v113
	v_lshlrev_b32_e32 v153, 16, v114
	v_and_b32_e32 v114, 0xffff0000, v114
	v_lshlrev_b32_e32 v154, 16, v115
	v_and_b32_e32 v115, 0xffff0000, v115
	v_add_f32_e32 v116, v116, v126
	v_add_f32_e32 v120, v120, v153
	v_add_f32_e32 v112, v117, v112
	v_add_f32_e32 v114, v121, v114
	v_add_f32_e32 v117, v118, v127
	v_add_f32_e32 v118, v122, v154
	v_add_f32_e32 v113, v119, v113
	v_add_f32_e32 v115, v123, v115
	v_add_f32_e32 v108, v108, v116
	v_add_f32_e32 v116, v104, v120
	v_add_f32_e32 v104, v109, v112
	v_add_f32_e32 v109, v105, v114
	v_add_f32_e32 v105, v110, v117
	v_add_f32_e32 v110, v106, v118
	v_add_f32_e32 v106, v111, v113
	v_add_f32_e32 v107, v107, v115
	v_cvt_pk_bf16_f32 v104, v108, v104
	v_cvt_pk_bf16_f32 v105, v105, v106
	v_cvt_pk_bf16_f32 v106, v116, v109
	v_cvt_pk_bf16_f32 v107, v110, v107
	global_load_dwordx4 v[108:111], v[160:161], off offset:256
	v_lshl_add_u64 v[116:117], v[146:147], 0, s[24:25]
	global_store_dwordx4 v[160:161], v[104:107], off
	global_load_dwordx4 v[104:107], v[124:125], off offset:512 nt
	s_nop 0
	global_load_dwordx4 v[112:115], v[124:125], off offset:528 nt
	v_lshl_add_u64 v[118:119], v[116:117], 1, s[30:31]
	s_waitcnt vmcnt(0)
; __device__ __forceinline__ unsigned pkbf(float lo, float hi) { return pg8::cvt_pk_bf16(lo, hi); }
; __device__ __forceinline__ void unpack8bf(const u32x4 w, float* f) { f[0] = bflo(w.x); f[1] = bfhi(w.x); f[2] = bflo(w.y); f[3] = bfhi(w.y); f[4] = bflo(w.z); f[5] = bfhi(w.z); f[6] = bflo(w.w); f[7] = bfhi(w.w); }
;     __device__ __forceinline__ void operator()(AccRef acc, const Unit& u, int wr, int wc, int fr, int fq) const {
;     ...
;                     const size_t off = (size_t)(row0 + ai * 128 + m * 16) * DM + col0 + bj * 128;
;                     const f32x4 x0 = *(const f32x4*)(xb + off), x1 = *(const f32x4*)(xb + off + 4);
;                     const u32x4 dw = *(const u32x4*)(D1 + off); float d[8]; unpack8bf(dw, d);
;                     float o[8];
; #pragma unroll
;                     for (int e = 0; e < 4; ++e) { o[e] = x0[e] + d[e] + acc[ai][bj][m][0][e]; o[4 + e] = x1[e] + d[4 + e] + acc[ai][bj][m][1][e]; }
;                     u32x4 w; w.x = pkbf(o[0], o[1]); w.y = pkbf(o[2], o[3]); w.z = pkbf(o[4], o[5]); w.w = pkbf(o[6], o[7]);
;                     *(u32x4*)(D1 + off) = w;
	v_lshlrev_b32_e32 v120, 16, v108
	v_and_b32_e32 v108, 0xffff0000, v108
	v_lshlrev_b32_e32 v121, 16, v109
	v_and_b32_e32 v109, 0xffff0000, v109
	v_lshlrev_b32_e32 v122, 16, v110
	v_and_b32_e32 v110, 0xffff0000, v110
	v_lshlrev_b32_e32 v123, 16, v111
	v_and_b32_e32 v111, 0xffff0000, v111
	v_add_f32_e32 v104, v104, v120
	v_add_f32_e32 v112, v112, v122
	v_add_f32_e32 v105, v105, v108
	v_add_f32_e32 v108, v113, v110
	v_add_f32_e32 v106, v106, v121
	v_add_f32_e32 v110, v114, v123
	v_add_f32_e32 v107, v107, v109
	v_add_f32_e32 v109, v115, v111
	v_add_f32_e32 v100, v100, v104
	v_add_f32_e32 v104, v96, v112
	v_add_f32_e32 v96, v101, v105
	v_add_f32_e32 v101, v97, v108
	v_add_f32_e32 v97, v102, v106
	v_add_f32_e32 v102, v98, v110
	v_add_f32_e32 v98, v103, v107
	v_add_f32_e32 v99, v99, v109
	v_cvt_pk_bf16_f32 v96, v100, v96
	v_cvt_pk_bf16_f32 v97, v97, v98
	v_cvt_pk_bf16_f32 v98, v104, v101
	v_cvt_pk_bf16_f32 v99, v102, v99
	global_store_dwordx4 v[160:161], v[96:99], off offset:256
	global_load_dwordx4 v[96:99], v[118:119], off
	v_lshl_add_u64 v[108:109], v[116:117], 2, s[4:5]
	global_load_dwordx4 v[100:103], v[108:109], off nt
	global_load_dwordx4 v[104:107], v[108:109], off offset:16 nt
	s_waitcnt vmcnt(0)
	v_lshlrev_b32_e32 v110, 16, v96
	v_and_b32_e32 v96, 0xffff0000, v96
	v_lshlrev_b32_e32 v111, 16, v97
	v_and_b32_e32 v97, 0xffff0000, v97
	v_lshlrev_b32_e32 v112, 16, v98
	v_and_b32_e32 v98, 0xffff0000, v98
	v_lshlrev_b32_e32 v113, 16, v99
	v_and_b32_e32 v99, 0xffff0000, v99
	v_add_f32_e32 v100, v100, v110
	v_add_f32_e32 v104, v104, v112
	v_add_f32_e32 v96, v101, v96
	v_add_f32_e32 v98, v105, v98
	v_add_f32_e32 v101, v102, v111
	v_add_f32_e32 v102, v106, v113
	v_add_f32_e32 v97, v103, v97
	v_add_f32_e32 v99, v107, v99
	v_add_f32_e32 v92, v92, v100
	v_add_f32_e32 v100, v88, v104
	v_add_f32_e32 v88, v93, v96
	v_add_f32_e32 v93, v89, v98
	v_add_f32_e32 v89, v94, v101
	v_add_f32_e32 v94, v90, v102
	v_add_f32_e32 v90, v95, v97
	v_add_f32_e32 v91, v91, v99
	v_cvt_pk_bf16_f32 v88, v92, v88
	v_cvt_pk_bf16_f32 v89, v89, v90
	v_cvt_pk_bf16_f32 v90, v100, v93
	v_cvt_pk_bf16_f32 v91, v94, v91
	global_load_dwordx4 v[92:95], v[118:119], off offset:256
	v_lshl_add_u64 v[100:101], v[146:147], 0, s[26:27]
	global_store_dwordx4 v[118:119], v[88:91], off
	global_load_dwordx4 v[88:91], v[108:109], off offset:512 nt
	s_nop 0
	global_load_dwordx4 v[96:99], v[108:109], off offset:528 nt
	v_lshl_add_u64 v[102:103], v[100:101], 1, s[30:31]
	s_waitcnt vmcnt(0)
	v_lshlrev_b32_e32 v104, 16, v92
	v_and_b32_e32 v92, 0xffff0000, v92
	v_lshlrev_b32_e32 v105, 16, v93
	v_and_b32_e32 v93, 0xffff0000, v93
	v_lshlrev_b32_e32 v106, 16, v94
	v_and_b32_e32 v94, 0xffff0000, v94
	v_lshlrev_b32_e32 v107, 16, v95
	v_and_b32_e32 v95, 0xffff0000, v95
	v_add_f32_e32 v88, v88, v104
	v_add_f32_e32 v96, v96, v106
	v_add_f32_e32 v89, v89, v92
	v_add_f32_e32 v92, v97, v94
	v_add_f32_e32 v90, v90, v105
	v_add_f32_e32 v94, v98, v107
	v_add_f32_e32 v91, v91, v93
	v_add_f32_e32 v93, v99, v95
	v_add_f32_e32 v84, v84, v88
	v_add_f32_e32 v88, v80, v96
	v_add_f32_e32 v80, v85, v89
	v_add_f32_e32 v85, v81, v92
	v_add_f32_e32 v81, v86, v90
	v_add_f32_e32 v86, v82, v94
	v_add_f32_e32 v82, v87, v91
	v_add_f32_e32 v83, v83, v93
	v_cvt_pk_bf16_f32 v80, v84, v80
	v_cvt_pk_bf16_f32 v81, v81, v82
	v_cvt_pk_bf16_f32 v82, v88, v85
	v_cvt_pk_bf16_f32 v83, v86, v83
	global_store_dwordx4 v[118:119], v[80:83], off offset:256
	global_load_dwordx4 v[80:83], v[102:103], off
	v_lshl_add_u64 v[92:93], v[100:101], 2, s[4:5]
	global_load_dwordx4 v[84:87], v[92:93], off nt
	global_load_dwordx4 v[88:91], v[92:93], off offset:16 nt
	s_waitcnt vmcnt(0)
	v_lshlrev_b32_e32 v94, 16, v80
	v_and_b32_e32 v80, 0xffff0000, v80
	v_lshlrev_b32_e32 v95, 16, v81
	v_and_b32_e32 v81, 0xffff0000, v81
	v_lshlrev_b32_e32 v96, 16, v82
	v_and_b32_e32 v82, 0xffff0000, v82
	v_lshlrev_b32_e32 v97, 16, v83
	v_and_b32_e32 v83, 0xffff0000, v83
	v_add_f32_e32 v84, v84, v94
	v_add_f32_e32 v88, v88, v96
	v_add_f32_e32 v80, v85, v80
	v_add_f32_e32 v82, v89, v82
	v_add_f32_e32 v85, v86, v95
	v_add_f32_e32 v86, v90, v97
	v_add_f32_e32 v81, v87, v81
	v_add_f32_e32 v83, v91, v83
	v_add_f32_e32 v76, v76, v84
	v_add_f32_e32 v84, v72, v88
	v_add_f32_e32 v72, v77, v80
	v_add_f32_e32 v77, v73, v82
	v_add_f32_e32 v73, v78, v85
	v_add_f32_e32 v78, v74, v86
	v_add_f32_e32 v74, v79, v81
	v_add_f32_e32 v75, v75, v83
	v_cvt_pk_bf16_f32 v72, v76, v72
	v_cvt_pk_bf16_f32 v73, v73, v74
	v_cvt_pk_bf16_f32 v74, v84, v77
	v_cvt_pk_bf16_f32 v75, v78, v75
	global_load_dwordx4 v[76:79], v[102:103], off offset:256
	v_lshl_add_u64 v[84:85], v[146:147], 0, s[28:29]
	global_store_dwordx4 v[102:103], v[72:75], off
	global_load_dwordx4 v[72:75], v[92:93], off offset:512 nt
	s_nop 0
	global_load_dwordx4 v[80:83], v[92:93], off offset:528 nt
	v_lshl_add_u64 v[86:87], v[84:85], 1, s[30:31]
	s_waitcnt vmcnt(0)
	v_lshlrev_b32_e32 v88, 16, v76
	v_and_b32_e32 v76, 0xffff0000, v76
	v_lshlrev_b32_e32 v89, 16, v77
	v_and_b32_e32 v77, 0xffff0000, v77
	v_lshlrev_b32_e32 v90, 16, v78
	v_and_b32_e32 v78, 0xffff0000, v78
	v_lshlrev_b32_e32 v91, 16, v79
	v_and_b32_e32 v79, 0xffff0000, v79
	v_add_f32_e32 v72, v72, v88
	v_add_f32_e32 v80, v80, v90
	v_add_f32_e32 v73, v73, v76
	v_add_f32_e32 v76, v81, v78
	v_add_f32_e32 v74, v74, v89
	v_add_f32_e32 v78, v82, v91
	v_add_f32_e32 v75, v75, v77
	v_add_f32_e32 v77, v83, v79
	v_add_f32_e32 v68, v68, v72
	v_add_f32_e32 v72, v64, v80
	v_add_f32_e32 v64, v69, v73
	v_add_f32_e32 v69, v65, v76
	v_add_f32_e32 v65, v70, v74
	v_add_f32_e32 v70, v66, v78
	v_add_f32_e32 v66, v71, v75
	v_add_f32_e32 v67, v67, v77
	v_cvt_pk_bf16_f32 v64, v68, v64
	v_cvt_pk_bf16_f32 v65, v65, v66
	v_cvt_pk_bf16_f32 v66, v72, v69
	v_cvt_pk_bf16_f32 v67, v70, v67
	global_store_dwordx4 v[102:103], v[64:67], off offset:256
	global_load_dwordx4 v[64:67], v[86:87], off
	v_lshl_add_u64 v[76:77], v[84:85], 2, s[4:5]
	global_load_dwordx4 v[68:71], v[76:77], off nt
	global_load_dwordx4 v[72:75], v[76:77], off offset:16 nt
	s_waitcnt vmcnt(0)
; __device__ __forceinline__ unsigned pkbf(float lo, float hi) { return pg8::cvt_pk_bf16(lo, hi); }
; __device__ __forceinline__ void unpack8bf(const u32x4 w, float* f) { f[0] = bflo(w.x); f[1] = bfhi(w.x); f[2] = bflo(w.y); f[3] = bfhi(w.y); f[4] = bflo(w.z); f[5] = bfhi(w.z); f[6] = bflo(w.w); f[7] = bfhi(w.w); }
;     __device__ __forceinline__ void operator()(AccRef acc, const Unit& u, int wr, int wc, int fr, int fq) const {
;     ...
;                     const size_t off = (size_t)(row0 + ai * 128 + m * 16) * DM + col0 + bj * 128;
;                     const f32x4 x0 = *(const f32x4*)(xb + off), x1 = *(const f32x4*)(xb + off + 4);
;                     const u32x4 dw = *(const u32x4*)(D1 + off); float d[8]; unpack8bf(dw, d);
;                     float o[8];
; #pragma unroll
;                     for (int e = 0; e < 4; ++e) { o[e] = x0[e] + d[e] + acc[ai][bj][m][0][e]; o[4 + e] = x1[e] + d[4 + e] + acc[ai][bj][m][1][e]; }
;                     u32x4 w; w.x = pkbf(o[0], o[1]); w.y = pkbf(o[2], o[3]); w.z = pkbf(o[4], o[5]); w.w = pkbf(o[6], o[7]);
;                     *(u32x4*)(D1 + off) = w;
	v_lshlrev_b32_e32 v78, 16, v64
	v_and_b32_e32 v64, 0xffff0000, v64
	v_lshlrev_b32_e32 v79, 16, v65
	v_and_b32_e32 v65, 0xffff0000, v65
	v_lshlrev_b32_e32 v80, 16, v66
	v_and_b32_e32 v66, 0xffff0000, v66
	v_lshlrev_b32_e32 v81, 16, v67
	v_and_b32_e32 v67, 0xffff0000, v67
	v_add_f32_e32 v68, v68, v78
	v_add_f32_e32 v72, v72, v80
	v_add_f32_e32 v64, v69, v64
	v_add_f32_e32 v66, v73, v66
	v_add_f32_e32 v69, v70, v79
	v_add_f32_e32 v70, v74, v81
	v_add_f32_e32 v65, v71, v65
	v_add_f32_e32 v67, v75, v67
	v_add_f32_e32 v60, v60, v68
	v_add_f32_e32 v68, v56, v72
	v_add_f32_e32 v56, v61, v64
	v_add_f32_e32 v61, v57, v66
	v_add_f32_e32 v57, v62, v69
	v_add_f32_e32 v62, v58, v70
	v_add_f32_e32 v58, v63, v65
	v_add_f32_e32 v59, v59, v67
	v_cvt_pk_bf16_f32 v56, v60, v56
	v_cvt_pk_bf16_f32 v57, v57, v58
	v_cvt_pk_bf16_f32 v58, v68, v61
	v_cvt_pk_bf16_f32 v59, v62, v59
	global_load_dwordx4 v[60:63], v[86:87], off offset:256
	v_lshl_add_u64 v[68:69], v[146:147], 0, s[36:37]
	global_store_dwordx4 v[86:87], v[56:59], off
	global_load_dwordx4 v[56:59], v[76:77], off offset:512 nt
	s_nop 0
	global_load_dwordx4 v[64:67], v[76:77], off offset:528 nt
	v_lshl_add_u64 v[70:71], v[68:69], 1, s[30:31]
	s_waitcnt vmcnt(0)
	v_lshlrev_b32_e32 v72, 16, v60
	v_and_b32_e32 v60, 0xffff0000, v60
	v_lshlrev_b32_e32 v73, 16, v61
	v_and_b32_e32 v61, 0xffff0000, v61
	v_lshlrev_b32_e32 v74, 16, v62
	v_and_b32_e32 v62, 0xffff0000, v62
	v_lshlrev_b32_e32 v75, 16, v63
	v_and_b32_e32 v63, 0xffff0000, v63
	v_add_f32_e32 v56, v56, v72
	v_add_f32_e32 v64, v64, v74
	v_add_f32_e32 v57, v57, v60
	v_add_f32_e32 v60, v65, v62
	v_add_f32_e32 v58, v58, v73
	v_add_f32_e32 v62, v66, v75
	v_add_f32_e32 v59, v59, v61
	v_add_f32_e32 v61, v67, v63
	v_add_f32_e32 v52, v52, v56
	v_add_f32_e32 v56, v48, v64
	v_add_f32_e32 v48, v53, v57
	v_add_f32_e32 v53, v49, v60
	v_add_f32_e32 v49, v54, v58
	v_add_f32_e32 v54, v50, v62
	v_add_f32_e32 v50, v55, v59
	v_add_f32_e32 v51, v51, v61
	v_cvt_pk_bf16_f32 v48, v52, v48
	v_cvt_pk_bf16_f32 v49, v49, v50
	v_cvt_pk_bf16_f32 v50, v56, v53
	v_cvt_pk_bf16_f32 v51, v54, v51
	global_store_dwordx4 v[86:87], v[48:51], off offset:256
	global_load_dwordx4 v[48:51], v[70:71], off
	v_lshl_add_u64 v[60:61], v[68:69], 2, s[4:5]
	global_load_dwordx4 v[52:55], v[60:61], off nt
	global_load_dwordx4 v[56:59], v[60:61], off offset:16 nt
	s_waitcnt vmcnt(0)
	v_lshlrev_b32_e32 v62, 16, v48
	v_and_b32_e32 v48, 0xffff0000, v48
	v_lshlrev_b32_e32 v63, 16, v49
	v_and_b32_e32 v49, 0xffff0000, v49
	v_lshlrev_b32_e32 v64, 16, v50
	v_and_b32_e32 v50, 0xffff0000, v50
	v_lshlrev_b32_e32 v65, 16, v51
	v_and_b32_e32 v51, 0xffff0000, v51
	v_add_f32_e32 v52, v52, v62
	v_add_f32_e32 v56, v56, v64
	v_add_f32_e32 v48, v53, v48
	v_add_f32_e32 v50, v57, v50
	v_add_f32_e32 v53, v54, v63
	v_add_f32_e32 v54, v58, v65
	v_add_f32_e32 v49, v55, v49
	v_add_f32_e32 v51, v59, v51
	v_add_f32_e32 v44, v44, v52
	v_add_f32_e32 v52, v40, v56
	v_add_f32_e32 v40, v45, v48
	v_add_f32_e32 v45, v41, v50
	v_add_f32_e32 v41, v46, v53
	v_add_f32_e32 v46, v42, v54
	v_add_f32_e32 v42, v47, v49
	v_add_f32_e32 v43, v43, v51
	v_cvt_pk_bf16_f32 v40, v44, v40
	v_cvt_pk_bf16_f32 v41, v41, v42
	v_cvt_pk_bf16_f32 v42, v52, v45
	v_cvt_pk_bf16_f32 v43, v46, v43
	global_load_dwordx4 v[44:47], v[70:71], off offset:256
	v_lshl_add_u64 v[52:53], v[146:147], 0, s[40:41]
	global_store_dwordx4 v[70:71], v[40:43], off
	global_load_dwordx4 v[40:43], v[60:61], off offset:512 nt
	s_nop 0
	global_load_dwordx4 v[48:51], v[60:61], off offset:528 nt
	v_lshl_add_u64 v[54:55], v[52:53], 1, s[30:31]
	s_waitcnt vmcnt(0)
	v_lshlrev_b32_e32 v56, 16, v44
	v_and_b32_e32 v44, 0xffff0000, v44
	v_lshlrev_b32_e32 v57, 16, v45
	v_and_b32_e32 v45, 0xffff0000, v45
	v_lshlrev_b32_e32 v58, 16, v46
	v_and_b32_e32 v46, 0xffff0000, v46
	v_lshlrev_b32_e32 v59, 16, v47
	v_and_b32_e32 v47, 0xffff0000, v47
	v_add_f32_e32 v40, v40, v56
	v_add_f32_e32 v48, v48, v58
	v_add_f32_e32 v41, v41, v44
	v_add_f32_e32 v44, v49, v46
	v_add_f32_e32 v42, v42, v57
	v_add_f32_e32 v46, v50, v59
	v_add_f32_e32 v43, v43, v45
	v_add_f32_e32 v45, v51, v47
	v_add_f32_e32 v36, v36, v40
	v_add_f32_e32 v40, v32, v48
	v_add_f32_e32 v32, v37, v41
	v_add_f32_e32 v37, v33, v44
	v_add_f32_e32 v33, v38, v42
	v_add_f32_e32 v38, v34, v46
	v_add_f32_e32 v34, v39, v43
	v_add_f32_e32 v35, v35, v45
	v_cvt_pk_bf16_f32 v32, v36, v32
	v_cvt_pk_bf16_f32 v33, v33, v34
	v_cvt_pk_bf16_f32 v34, v40, v37
	v_cvt_pk_bf16_f32 v35, v38, v35
	global_store_dwordx4 v[70:71], v[32:35], off offset:256
	global_load_dwordx4 v[32:35], v[54:55], off
	v_lshl_add_u64 v[44:45], v[52:53], 2, s[4:5]
	global_load_dwordx4 v[36:39], v[44:45], off nt
	global_load_dwordx4 v[40:43], v[44:45], off offset:16 nt
	s_waitcnt vmcnt(0)
; #define PG8_BAR __builtin_amdgcn_s_barrier()
; __device__ __forceinline__ unsigned pkbf(float lo, float hi) { return pg8::cvt_pk_bf16(lo, hi); }
; __device__ __forceinline__ void unpack8bf(const u32x4 w, float* f) { f[0] = bflo(w.x); f[1] = bfhi(w.x); f[2] = bflo(w.y); f[3] = bfhi(w.y); f[4] = bflo(w.z); f[5] = bfhi(w.z); f[6] = bflo(w.w); f[7] = bfhi(w.w); }
; template <class Epi, class Sched, bool ALIGN_EPI = false, bool SP2 = false>
; __device__ __forceinline__ void gemm_phase(PG8_LAS unsigned char* lds, const Gemm g, const Sched& S, const Epi& E) {
;     ...
;         if constexpr (ALIGN_EPI) { if (wr == 0) PG8_BAR; }
;         if constexpr (!Epi::AFTER_DRAIN) { E(acc, cur, wr, wc, fr, fq); S.done(cur); }
;         if (!has_next) break;
; #pragma unroll
;         for (int a = 0; a < 2; ++a)
; #pragma unroll
;             for (int b = 0; b < 2; ++b)
; #pragma unroll
;                 for (int m = 0; m < 4; ++m)
; #pragma unroll
;                     for (int n = 0; n < 2; ++n) acc[a][b][m][n] = (f32x4){0.f, 0.f, 0.f, 0.f};
;         cur = nxt; cA = nA; cB = nB; ++ui;
;         if constexpr (ALIGN_EPI) { if (wr == 1) PG8_BAR; }
;     }
;     __device__ __forceinline__ void operator()(AccRef acc, const Unit& u, int wr, int wc, int fr, int fq) const {
;     ...
;                     const size_t off = (size_t)(row0 + ai * 128 + m * 16) * DM + col0 + bj * 128;
;                     const f32x4 x0 = *(const f32x4*)(xb + off), x1 = *(const f32x4*)(xb + off + 4);
;                     const u32x4 dw = *(const u32x4*)(D1 + off); float d[8]; unpack8bf(dw, d);
;                     float o[8];
; #pragma unroll
;                     for (int e = 0; e < 4; ++e) { o[e] = x0[e] + d[e] + acc[ai][bj][m][0][e]; o[4 + e] = x1[e] + d[4 + e] + acc[ai][bj][m][1][e]; }
;                     u32x4 w; w.x = pkbf(o[0], o[1]); w.y = pkbf(o[2], o[3]); w.z = pkbf(o[4], o[5]); w.w = pkbf(o[6], o[7]);
;                     *(u32x4*)(D1 + off) = w;
	v_lshlrev_b32_e32 v46, 16, v32
	v_and_b32_e32 v32, 0xffff0000, v32
	v_lshlrev_b32_e32 v47, 16, v33
	v_and_b32_e32 v33, 0xffff0000, v33
	v_lshlrev_b32_e32 v48, 16, v34
	v_and_b32_e32 v34, 0xffff0000, v34
	v_lshlrev_b32_e32 v49, 16, v35
	v_and_b32_e32 v35, 0xffff0000, v35
	v_add_f32_e32 v36, v36, v46
	v_add_f32_e32 v40, v40, v48
	v_add_f32_e32 v32, v37, v32
	v_add_f32_e32 v34, v41, v34
	v_add_f32_e32 v37, v38, v47
	v_add_f32_e32 v38, v42, v49
	v_add_f32_e32 v33, v39, v33
	v_add_f32_e32 v35, v43, v35
	v_add_f32_e32 v28, v28, v36
	v_add_f32_e32 v36, v24, v40
	v_add_f32_e32 v24, v29, v32
	v_add_f32_e32 v29, v25, v34
	v_add_f32_e32 v25, v30, v37
	v_add_f32_e32 v30, v26, v38
	v_add_f32_e32 v26, v31, v33
	v_add_f32_e32 v27, v27, v35
	v_cvt_pk_bf16_f32 v24, v28, v24
	v_cvt_pk_bf16_f32 v25, v25, v26
	v_cvt_pk_bf16_f32 v26, v36, v29
	v_cvt_pk_bf16_f32 v27, v30, v27
	global_load_dwordx4 v[28:31], v[54:55], off offset:256
	v_lshl_add_u64 v[36:37], v[146:147], 0, s[42:43]
	global_store_dwordx4 v[54:55], v[24:27], off
	global_load_dwordx4 v[24:27], v[44:45], off offset:512 nt
	s_nop 0
	global_load_dwordx4 v[32:35], v[44:45], off offset:528 nt
	v_lshl_add_u64 v[38:39], v[36:37], 1, s[30:31]
	s_waitcnt vmcnt(0)
	v_lshlrev_b32_e32 v40, 16, v28
	v_and_b32_e32 v28, 0xffff0000, v28
	v_lshlrev_b32_e32 v41, 16, v29
	v_and_b32_e32 v29, 0xffff0000, v29
	v_lshlrev_b32_e32 v42, 16, v30
	v_and_b32_e32 v30, 0xffff0000, v30
	v_lshlrev_b32_e32 v43, 16, v31
	v_and_b32_e32 v31, 0xffff0000, v31
	v_add_f32_e32 v24, v24, v40
	v_add_f32_e32 v32, v32, v42
	v_add_f32_e32 v25, v25, v28
	v_add_f32_e32 v28, v33, v30
	v_add_f32_e32 v26, v26, v41
	v_add_f32_e32 v30, v34, v43
	v_add_f32_e32 v27, v27, v29
	v_add_f32_e32 v29, v35, v31
	v_add_f32_e32 v20, v20, v24
	v_add_f32_e32 v24, v16, v32
	v_add_f32_e32 v16, v21, v25
	v_add_f32_e32 v21, v17, v28
	v_add_f32_e32 v17, v22, v26
	v_add_f32_e32 v22, v18, v30
	v_add_f32_e32 v18, v23, v27
	v_add_f32_e32 v19, v19, v29
	v_cvt_pk_bf16_f32 v16, v20, v16
	v_cvt_pk_bf16_f32 v17, v17, v18
	v_cvt_pk_bf16_f32 v18, v24, v21
	v_cvt_pk_bf16_f32 v19, v22, v19
	global_store_dwordx4 v[54:55], v[16:19], off offset:256
	global_load_dwordx4 v[16:19], v[38:39], off
	v_lshl_add_u64 v[28:29], v[36:37], 2, s[4:5]
	global_load_dwordx4 v[20:23], v[28:29], off nt
	global_load_dwordx4 v[24:27], v[28:29], off offset:16 nt
	s_mov_b64 s[4:5], -1
	s_waitcnt vmcnt(0)
	v_lshlrev_b32_e32 v30, 16, v16
	v_and_b32_e32 v16, 0xffff0000, v16
	v_lshlrev_b32_e32 v31, 16, v17
	v_and_b32_e32 v17, 0xffff0000, v17
	v_lshlrev_b32_e32 v32, 16, v18
	v_and_b32_e32 v18, 0xffff0000, v18
	v_lshlrev_b32_e32 v33, 16, v19
	v_and_b32_e32 v19, 0xffff0000, v19
	v_add_f32_e32 v20, v20, v30
	v_add_f32_e32 v24, v24, v32
	v_add_f32_e32 v16, v21, v16
	v_add_f32_e32 v18, v25, v18
	v_add_f32_e32 v21, v22, v31
	v_add_f32_e32 v22, v26, v33
	v_add_f32_e32 v17, v23, v17
	v_add_f32_e32 v19, v27, v19
	v_add_f32_e32 v12, v12, v20
	v_add_f32_e32 v20, v8, v24
	v_add_f32_e32 v8, v13, v16
	v_add_f32_e32 v13, v9, v18
	v_add_f32_e32 v9, v14, v21
	v_add_f32_e32 v14, v10, v22
	v_add_f32_e32 v10, v15, v17
	v_add_f32_e32 v11, v11, v19
	v_cvt_pk_bf16_f32 v8, v12, v8
	v_cvt_pk_bf16_f32 v9, v9, v10
	v_cvt_pk_bf16_f32 v10, v20, v13
	v_cvt_pk_bf16_f32 v11, v14, v11
	global_load_dwordx4 v[12:15], v[38:39], off offset:256
	s_waitcnt vmcnt(0)
	v_lshlrev_b32_e32 v20, 16, v12
	global_store_dwordx4 v[38:39], v[8:11], off
	global_load_dwordx4 v[8:11], v[28:29], off offset:512 nt
	s_nop 0
	global_load_dwordx4 v[16:19], v[28:29], off offset:528 nt
	v_and_b32_e32 v12, 0xffff0000, v12
	v_lshlrev_b32_e32 v21, 16, v13
	v_and_b32_e32 v13, 0xffff0000, v13
	v_lshlrev_b32_e32 v22, 16, v14
	v_and_b32_e32 v14, 0xffff0000, v14
	v_lshlrev_b32_e32 v23, 16, v15
	v_and_b32_e32 v15, 0xffff0000, v15
	s_waitcnt vmcnt(0)
	v_add_f32_e32 v8, v8, v20
	v_add_f32_e32 v16, v16, v22
	v_add_f32_e32 v9, v9, v12
	v_add_f32_e32 v12, v17, v14
	v_add_f32_e32 v10, v10, v21
	v_add_f32_e32 v14, v18, v23
	v_add_f32_e32 v11, v11, v13
	v_add_f32_e32 v13, v19, v15
	v_add_f32_e32 v4, v4, v8
	v_add_f32_e32 v8, v0, v16
	v_add_f32_e32 v0, v5, v9
	v_add_f32_e32 v5, v1, v12
	v_add_f32_e32 v1, v6, v10
	v_add_f32_e32 v6, v2, v14
	v_add_f32_e32 v2, v7, v11
	v_add_f32_e32 v3, v3, v13
	v_cvt_pk_bf16_f32 v0, v4, v0
	v_cvt_pk_bf16_f32 v1, v1, v2
	v_cvt_pk_bf16_f32 v2, v8, v5
	v_cvt_pk_bf16_f32 v3, v6, v3
	global_store_dwordx4 v[38:39], v[0:3], off offset:256
	s_cbranch_vccnz .LBB0_1234
	s_andn2_b64 vcc, exec, s[94:95]
	s_cbranch_vccnz .LBB0_1233
	s_barrier
	s_branch .LBB0_1233
